# A1 tile loop: static s_setprio 1 for the younger half (waves 4-7 stream), reset at loop exit
# baseline (speedup 1.0000x reference)
; #define B_LOADK(Kb_, tile_) do { const char* kp_ = (const char*)(Kb_) + (size_t)(tile_) * (64 * LDK * 2); const unsigned ko_ = ((tile_) == NT - 1) ? koffL : koff; \
;     _Pragma("unroll") for (int i_ = 0; i_ < NKC; ++i_) rk[i_] = *(const u32x4*)(kp_ + ko_ + i_ * 128); } while (0)
; #define B_LOADV(Vb_, tile_) do { const char* vp_ = (const char*)(Vb_) + (size_t)(tile_) * 128; \
;     rv[0] = *(const u32x4*)(vp_ + voff); rv[1] = *(const u32x4*)(vp_ + voff + 64 * LP * 2); } while (0)
; #define B_WRITEK(bi_) do { char* b_w = kb0 + (bi_) * KBYTES + kwoff; \
;     _Pragma("unroll") for (int i_ = 0; i_ < NKC; ++i_) *(u32x4*)(b_w + i_ * 128) = rk[i_]; } while (0)
; #define B_WRITEV(bi_) do { char* b_w = vb0 + (bi_) * VBYTES + vwoff; \
;     *(u32x4*)(b_w) = rv[0]; *(u32x4*)(b_w + 64 * VSTR) = rv[1]; } while (0)
; template <int NHQ, int NHKV>
; DI void attn_phase_l1(const u16* __restrict__ Q, const u16* __restrict__ K, const u16* __restrict__ Vt, u16* __restrict__ O, const float* __restrict__ qg, char* smem, const int wv) {
;     ...
;     for (int j = 0; j < NT; ++j) {
;       if (j + 2 < NT) B_WRITEK(j & 1);
;       if (j + 1 < NT) B_WRITEV((j + 1) & 1);
;       __builtin_amdgcn_sched_barrier(0);
;       if (j + 3 < NT) B_LOADK(Kb, j + 3);
;       if (j + 2 < NT) B_LOADV(Vb, j + 2);
;       __builtin_amdgcn_sched_barrier(0);
;       if (j == NT - 1) {
.Lb_first:
	s_setprio 1
	v_mov_b32_e32 v156, v92
	v_mov_b32_e32 v152, v88
	v_mov_b32_e32 v148, v84
	v_mov_b32_e32 v144, v80
	s_branch .Lb_body
	.p2align 3

; DI unsigned cvtpk(float lo, float hi) { f32x2 v = {lo, hi}; return __builtin_bit_cast(unsigned, __builtin_convertvector(v, bf16x2_t)); }
; template <int NHQ, int NHKV>
; DI void attn_phase_l1(const u16* __restrict__ Q, const u16* __restrict__ K, const u16* __restrict__ Vt, u16* __restrict__ O, const float* __restrict__ qg, char* smem, const int wv) {
;     ...
;       unsigned w_[16]; f32x2 ps2 = {0.f, 0.f};
; #pragma unroll
;       for (int i = 0; i < 8; ++i) { f32x2 v; v[0] = __builtin_amdgcn_exp2f(s0[2 * i]); v[1] = __builtin_amdgcn_exp2f(s0[2 * i + 1]); ps2 += v; w_[i] = cvtpk(v[0], v[1]); }
; #pragma unroll
;       for (int i = 0; i < 8; ++i) { f32x2 v; v[0] = __builtin_amdgcn_exp2f(s1[2 * i]); v[1] = __builtin_amdgcn_exp2f(s1[2 * i + 1]); ps2 += v; w_[8 + i] = cvtpk(v[0], v[1]); }
;       l += ps2[0] + ps2[1];
; #pragma unroll
;       for (int q = 0; q < 4; ++q) pb[q] = __builtin_bit_cast(bf16x8, u32x4{w_[4 * q], w_[4 * q + 1], w_[4 * q + 2], w_[4 * q + 3]});
.Lb_exit:
	s_nop 7
	v_exp_f32_e32 v246, v80
	v_exp_f32_e32 v247, v81
	s_nop 0
	v_add_f32_e32 v250, 0, v246
	v_add_f32_e32 v251, 0, v247
	v_exp_f32_e32 v248, v82
	v_exp_f32_e32 v249, v83
	v_cvt_pk_bf16_f32 v80, v246, v247
	v_add_f32_e32 v250, v248, v250
	v_add_f32_e32 v251, v249, v251
	v_exp_f32_e32 v246, v84
	v_exp_f32_e32 v247, v85
	v_cvt_pk_bf16_f32 v145, v248, v249
	v_add_f32_e32 v250, v246, v250
	v_add_f32_e32 v251, v247, v251
	v_exp_f32_e32 v248, v86
	v_exp_f32_e32 v249, v87
	v_cvt_pk_bf16_f32 v146, v246, v247
	v_add_f32_e32 v250, v248, v250
	v_add_f32_e32 v251, v249, v251
	v_exp_f32_e32 v246, v88
	v_exp_f32_e32 v247, v89
	v_cvt_pk_bf16_f32 v147, v248, v249
	v_add_f32_e32 v250, v246, v250
	v_add_f32_e32 v251, v247, v251
	v_exp_f32_e32 v248, v90
	v_exp_f32_e32 v249, v91
	v_cvt_pk_bf16_f32 v84, v246, v247
	v_add_f32_e32 v250, v248, v250
	v_add_f32_e32 v251, v249, v251
	v_exp_f32_e32 v246, v92
	v_exp_f32_e32 v247, v93
	v_cvt_pk_bf16_f32 v149, v248, v249
	v_add_f32_e32 v250, v246, v250
	v_add_f32_e32 v251, v247, v251
	v_exp_f32_e32 v248, v94
	v_exp_f32_e32 v249, v95
	v_cvt_pk_bf16_f32 v150, v246, v247
	v_add_f32_e32 v250, v248, v250
	v_add_f32_e32 v251, v249, v251
	v_exp_f32_e32 v246, v64
	v_exp_f32_e32 v247, v65
	v_cvt_pk_bf16_f32 v151, v248, v249
	v_add_f32_e32 v250, v246, v250
	v_add_f32_e32 v251, v247, v251
	v_exp_f32_e32 v248, v66
	v_exp_f32_e32 v249, v67
	v_cvt_pk_bf16_f32 v88, v246, v247
	v_add_f32_e32 v250, v248, v250
	v_add_f32_e32 v251, v249, v251
	v_exp_f32_e32 v246, v68
	v_exp_f32_e32 v247, v69
	v_cvt_pk_bf16_f32 v153, v248, v249
	v_add_f32_e32 v250, v246, v250
	v_add_f32_e32 v251, v247, v251
	v_exp_f32_e32 v248, v70
	v_exp_f32_e32 v249, v71
	v_cvt_pk_bf16_f32 v154, v246, v247
	v_add_f32_e32 v250, v248, v250
	v_add_f32_e32 v251, v249, v251
	v_exp_f32_e32 v246, v72
	v_exp_f32_e32 v247, v73
	v_cvt_pk_bf16_f32 v155, v248, v249
	v_add_f32_e32 v250, v246, v250
	v_add_f32_e32 v251, v247, v251
	v_exp_f32_e32 v248, v74
	v_exp_f32_e32 v249, v75
	v_cvt_pk_bf16_f32 v92, v246, v247
	v_add_f32_e32 v250, v248, v250
	v_add_f32_e32 v251, v249, v251
	v_exp_f32_e32 v246, v76
	v_exp_f32_e32 v247, v77
	v_cvt_pk_bf16_f32 v157, v248, v249
	v_add_f32_e32 v250, v246, v250
	v_add_f32_e32 v251, v247, v251
	v_exp_f32_e32 v248, v78
	v_exp_f32_e32 v249, v79
	v_cvt_pk_bf16_f32 v158, v246, v247
	v_add_f32_e32 v250, v248, v250
	v_add_f32_e32 v251, v249, v251
	v_cvt_pk_bf16_f32 v159, v248, v249
	v_add_f32_e32 v250, v250, v251
	v_add_f32_e32 v176, v176, v250
	s_setprio 0
	s_branch .LBB0_1215
